# stack1d + ssqA pointer kept in SGPRs for in_even/in_odd epilogues (kernarg and rstd load latencies overlapped)
# speedup vs baseline: 1.0073x; 1.0073x over previous
; #define LAS __attribute__((address_space(3)))
;     __host__ __device__ bool next(int i, Unit& u) const {
;         const long L = (long)i * G + c; if (L >= nwg) return false;
;         int wgid = (int)L; { const int q = nwg / NXCD, r = nwg % NXCD, xcd = wgid % NXCD, off = wgid / NXCD; wgid = (xcd < r ? xcd * (q + 1) : r * (q + 1) + (xcd - r) * q) + off; }
;         const int nig = WGM * nN, gid = wgid / nig, fm = gid * WGM, gsz = (nM - fm) < WGM ? (nM - fm) : WGM;
;         u.pm = fm + ((wgid % nig) % gsz); u.pn = (wgid % nig) / gsz; return true;
; template <bool ALIGN = true, class Epi>
; __device__ __forceinline__ void run_gemm(LAS unsigned char* lds, const bf16_t* A, const bf16_t* Bt, int N, int K, const Epi& E) {
;   asm volatile("" : "+s"(N), "+s"(K));
;   pg8::Gemm g{A, Bt, NTOK, N, K};
;   pg8::StaticOrder S; S.init(NTOK, N, (int)gridDim.x, (int)blockIdx.x);
.LBB0_438:
	s_or_b64 exec, exec, s[46:47]
	s_load_dwordx2 s[98:99], s[0:1], 0xe8
	s_mov_b64 s[6:7], s[0:1]
	s_waitcnt lgkmcnt(0)
	s_barrier
	v_mov_b32_e32 v12, v254
	s_waitcnt vmcnt(0)
	v_mov_b64_e32 v[0:1], s[6:7]
	flat_load_dwordx2 v[140:141], v[0:1] offset:192
	flat_load_dwordx2 v[142:143], v[0:1] offset:392
	s_movk_i32 s7, 0x600
	s_movk_i32 s6, 0x400
	s_ashr_i32 s8, s7, 31
	s_lshr_b32 s8, s8, 24
	s_add_i32 s7, s7, s8
	s_ashr_i32 s12, s7, 8
	s_lshl_b32 s10, s12, 7
	s_cmp_lt_i32 s2, s10
	s_cselect_b64 s[8:9], -1, 0
	s_cmp_ge_i32 s2, s10
	v_readfirstlane_b32 s11, v12
	s_cbranch_scc1 .LBB0_440
	s_lshl_b32 s15, s12, 3
	s_abs_i32 s16, s15
	v_cvt_f32_u32_e32 v0, s16
	s_lshr_b32 s13, s3, 29
	s_add_i32 s13, s2, s13
	s_ashr_i32 s14, s13, 3
	v_rcp_iflag_f32_e32 v0, v0
	s_and_b32 s13, s13, -8
	s_sub_i32 s13, s2, s13
	s_lshl_b32 s7, s12, 4
	v_mul_f32_e32 v0, 0x4f7ffffe, v0
	v_cvt_u32_f32_e32 v0, v0
	s_lshr_b32 s17, s13, 31
	s_or_b32 s7, s7, s17
	s_sub_i32 s17, 0, s16
	v_readfirstlane_b32 s18, v0
	s_mul_i32 s7, s7, s13
	s_mul_i32 s17, s17, s18
	s_add_i32 s7, s7, s14
	s_mul_hi_u32 s17, s18, s17
	s_abs_i32 s14, s7
	s_add_i32 s18, s18, s17
	s_mul_hi_u32 s17, s14, s18
	s_mul_i32 s18, s17, s16
	s_xor_b32 s13, s7, s15
	s_sub_i32 s14, s14, s18
	s_ashr_i32 s13, s13, 31
	s_add_i32 s18, s17, 1
	s_sub_i32 s19, s14, s16
	s_cmp_ge_u32 s14, s16
	s_cselect_b32 s17, s18, s17
	s_cselect_b32 s14, s19, s14
	s_add_i32 s18, s17, 1
	s_cmp_ge_u32 s14, s16
	s_cselect_b32 s14, s18, s17
	s_xor_b32 s14, s14, s13
	s_sub_i32 s13, s14, s13
	s_lshl_b32 s14, s13, 3
	s_sub_i32 s16, 0x80, s14
	s_min_i32 s16, s16, 8
	s_abs_i32 s17, s16
	v_cvt_f32_u32_e32 v0, s17
	s_sub_i32 s18, 0, s17
	s_mul_i32 s13, s13, s15
	s_sub_i32 s7, s7, s13
	v_rcp_iflag_f32_e32 v0, v0
	s_abs_i32 s15, s7
	s_xor_b32 s13, s7, s16
	s_ashr_i32 s13, s13, 31
	v_mul_f32_e32 v0, 0x4f7ffffe, v0
	v_cvt_u32_f32_e32 v0, v0
	s_nop 0
	v_readfirstlane_b32 s19, v0
	s_mul_i32 s18, s18, s19
	s_mul_hi_u32 s18, s19, s18
	s_add_i32 s19, s19, s18
	s_mul_hi_u32 s18, s15, s19
	s_mul_i32 s19, s18, s17
	s_sub_i32 s15, s15, s19
	s_add_i32 s19, s18, 1
	s_sub_i32 s20, s15, s17
	s_cmp_ge_u32 s15, s17
	s_cselect_b32 s18, s19, s18
	s_cselect_b32 s15, s20, s15
	s_add_i32 s19, s18, 1
	s_cmp_ge_u32 s15, s17
	s_cselect_b32 s15, s19, s18
	s_xor_b32 s15, s15, s13
	s_sub_i32 s75, s15, s13
	s_mul_i32 s13, s75, s16
	s_sub_i32 s7, s7, s13
	s_add_i32 s14, s7, s14

; #define GAS __attribute__((address_space(1)))
; template <int NP>
; __device__ __forceinline__ void rows_rstd(const float* ssq, float invn, const Unit& u, int wr, int fr, int fq, float (&rs)[2][4]) {
; #pragma unroll
;   for (int ai = 0; ai < 2; ++ai)
; #pragma unroll
;     for (int m = 0; m < 4; ++m) {
;       const int row = erow(u, ai, wr, m, fr);
;       float s;
;       if (NP == 16) {
;         const f32x4 v = *(GAS const f32x4*)(ssq + (size_t)row * 16 + 4 * fq);
;         s = (v[0] + v[1]) + (v[2] + v[3]);
;         s += __shfl_xor(s, 16); s += __shfl_xor(s, 32);
;       } else {
;         const f32x4 v = *(GAS const f32x4*)(ssq + (size_t)row * 4);
;         s = (v[0] + v[1]) + (v[2] + v[3]);
;       }
;       rs[ai][m] = rsqrtf(s * invn + RMS_EPS);
;     }
;   __device__ __forceinline__ void operator()(ACC_T, const Unit& u, int wr, int wc, int fr, int fq) const {
;     if (u.pn == 5 && wc != 0) return;
;     const Params& P = kparams();
;     const float *ssq = P.ssqA, *rope = P.rope; bf16_t *Qa = P.Qa, *Ka = P.Ka, *Vta = P.Vta, *cqb = P.cqb, *ckvb = P.ckvb, *Kr = P.Kr; float *ssq_cq = P.ssq_cq, *ssq_ckv = P.ssq_ckv;
;     float rs[2][4]; rows_rstd<16>(ssq, 1.0f / DM, u, wr, fr, fq, rs);
; #pragma unroll
;     for (int ai = 0; ai < 2; ++ai)
; #pragma unroll
;       for (int m = 0; m < 4; ++m) {
;         const int row = erow(u, ai, wr, m, fr), b = row >> 12, s = row & (SEQ - 1); const float r = rs[ai][m];
.LBB0_457:
	s_cmp_eq_u32 s75, 5
	s_cselect_b64 s[12:13], -1, 0
	s_and_b64 s[12:13], s[30:31], s[12:13]
	s_and_b64 vcc, exec, s[12:13]
	s_cbranch_vccnz .LBB0_571
	s_mov_b64 s[12:13], s[0:1]
	s_lshl_b32 s51, s14, 8
	v_mov_b64_e32 v[182:183], s[12:13]
	v_mov_b64_e32 v[176:177], s[98:99]
	s_add_i32 s51, s51, s59
	v_or_b32_e32 v202, s51, v155
	v_or_b32_e32 v196, 16, v202
	v_mov_b32_e32 v165, v153
	v_ashrrev_i32_e32 v203, 31, v202
	v_or_b32_e32 v192, 32, v202
	v_add_u32_e32 v190, 0x80, v202
	v_ashrrev_i32_e32 v197, 31, v196
	v_lshlrev_b64 v[212:213], 6, v[202:203]
	v_ashrrev_i32_e32 v193, 31, v192
	v_ashrrev_i32_e32 v191, 31, v190
	v_lshlrev_b64 v[204:205], 6, v[196:197]
	v_or_b32_e32 v180, 48, v202
	v_add_u32_e32 v206, 0x90, v202
	v_lshlrev_b64 v[194:195], 6, v[192:193]
	v_lshlrev_b64 v[190:191], 6, v[190:191]
	flat_load_dwordx2 v[178:179], v[182:183] offset:456
	flat_load_dwordx4 v[128:131], v[182:183] offset:472
	flat_load_dwordx4 v[136:139], v[182:183] offset:504
	flat_load_dwordx4 v[132:135], v[182:183] offset:248
	v_ashrrev_i32_e32 v181, 31, v180
	v_ashrrev_i32_e32 v207, 31, v206
	v_add_u32_e32 v208, 0xa0, v202
	v_ashrrev_i32_e32 v209, 31, v208
	v_add_u32_e32 v214, 0xb0, v202
	v_ashrrev_i32_e32 v215, 31, v214
	s_cmp_gt_i32 s75, 1
	s_cselect_b64 s[46:47], -1, 0
	s_cmp_eq_u32 s75, 3
	v_mov_b32_e32 v167, v153
	v_mov_b32_e32 v169, v153
	s_mov_b64 s[48:49], -1
	v_lshl_add_u64 v[176:177], v[176:177], 0, v[164:165]
	v_lshl_add_u64 v[184:185], v[176:177], 0, v[212:213]
	v_lshl_add_u64 v[188:189], v[176:177], 0, v[204:205]
	global_load_dwordx4 v[184:187], v[184:185], off
	v_lshl_add_u64 v[190:191], v[176:177], 0, v[190:191]
	global_load_dwordx4 v[198:201], v[188:189], off
	v_lshl_add_u64 v[188:189], v[176:177], 0, v[194:195]
	global_load_dwordx4 v[220:223], v[188:189], off
	global_load_dwordx4 v[228:231], v[190:191], off
	v_lshlrev_b64 v[188:189], 6, v[180:181]
	v_lshlrev_b64 v[190:191], 6, v[206:207]
	v_lshl_add_u64 v[218:219], v[176:177], 0, v[188:189]
	v_lshl_add_u64 v[190:191], v[176:177], 0, v[190:191]
	global_load_dwordx4 v[224:227], v[218:219], off
	global_load_dwordx4 v[232:235], v[190:191], off
	v_lshlrev_b64 v[190:191], 6, v[208:209]
	v_lshl_add_u64 v[190:191], v[176:177], 0, v[190:191]
	global_load_dwordx4 v[236:239], v[190:191], off
	v_lshlrev_b64 v[190:191], 6, v[214:215]
	v_lshl_add_u64 v[176:177], v[176:177], 0, v[190:191]
	global_load_dwordx4 v[240:243], v[176:177], off
	s_nop 0
	flat_load_dwordx2 v[176:177], v[182:183] offset:280
	flat_load_dwordx2 v[206:207], v[182:183] offset:440
	v_and_b32_e32 v182, 64, v217
	v_xor_b32_e32 v165, 16, v217
	v_add_u32_e32 v182, 64, v182
	v_xor_b32_e32 v183, 32, v217
	v_cmp_lt_i32_e32 vcc, v165, v182
	s_waitcnt vmcnt(0)
	v_mov_b32_e32 v190, v229
	v_cndmask_b32_e32 v165, v217, v165, vcc
	v_cmp_lt_i32_e32 vcc, v183, v182
	v_lshlrev_b32_e32 v218, 2, v165
	v_mov_b32_e32 v191, v230
	v_cndmask_b32_e32 v182, v217, v183, vcc
	s_cselect_b64 vcc, -1, 0
	v_cndmask_b32_e32 v137, v139, v137, vcc
	v_cndmask_b32_e32 v136, v138, v136, vcc
	v_cndmask_b32_e32 v139, v135, v133, vcc
	v_cndmask_b32_e32 v138, v134, v132, vcc
	v_lshlrev_b32_e32 v165, 2, v182
	v_lshl_add_u64 v[182:183], v[130:131], 0, v[166:167]
	v_lshl_add_u64 v[134:135], v[128:129], 0, v[168:169]
	v_lshl_add_u64 v[130:131], v[136:137], 0, v[152:153]
	v_lshl_add_u64 v[128:129], v[138:139], 0, s[20:21]
	v_mov_b32_e32 v136, v185
	v_mov_b32_e32 v137, v186
	v_mov_b32_e32 v185, v187
	v_mov_b32_e32 v138, v199
	v_mov_b32_e32 v139, v200
	v_mov_b32_e32 v199, v201
	v_lshl_add_u64 v[132:133], v[178:179], 0, v[152:153]
	v_mov_b32_e32 v178, v221
	v_mov_b32_e32 v179, v222
	v_mov_b32_e32 v221, v223
	v_mov_b32_e32 v186, v225
	v_mov_b32_e32 v187, v226
	v_mov_b32_e32 v225, v227
	v_mov_b32_e32 v229, v231
	v_mov_b32_e32 v200, v233
	v_mov_b32_e32 v201, v234
	v_mov_b32_e32 v233, v235
	v_mov_b32_e32 v208, v237
	v_mov_b32_e32 v209, v238
	v_mov_b32_e32 v237, v239
	v_pk_add_f32 v[136:137], v[136:137], v[184:185]
	v_pk_add_f32 v[138:139], v[138:139], v[198:199]
	v_pk_add_f32 v[178:179], v[178:179], v[220:221]
	v_pk_add_f32 v[184:185], v[186:187], v[224:225]
	v_pk_add_f32 v[186:187], v[190:191], v[228:229]
	v_pk_add_f32 v[190:191], v[200:201], v[232:233]
	v_pk_add_f32 v[198:199], v[208:209], v[236:237]
	v_mov_b32_e32 v208, v138
	v_mov_b32_e32 v209, v136
	v_mov_b32_e32 v136, v139
	v_mov_b32_e32 v214, v241
	v_mov_b32_e32 v215, v242
	v_mov_b32_e32 v241, v243
	v_mov_b32_e32 v138, v184
	v_mov_b32_e32 v139, v178
	v_mov_b32_e32 v178, v185
	v_mov_b32_e32 v184, v190
	v_mov_b32_e32 v185, v186
	v_mov_b32_e32 v186, v191
	v_pk_add_f32 v[136:137], v[208:209], v[136:137]
	v_pk_add_f32 v[200:201], v[214:215], v[240:241]
	v_pk_add_f32 v[138:139], v[138:139], v[178:179]
	v_pk_add_f32 v[178:179], v[184:185], v[186:187]
	ds_bpermute_b32 v185, v218, v137
	ds_bpermute_b32 v184, v218, v136
	v_mov_b32_e32 v190, v200
	v_mov_b32_e32 v191, v198
	v_mov_b32_e32 v198, v201
	ds_bpermute_b32 v201, v218, v179
	ds_bpermute_b32 v200, v218, v178
	s_waitcnt lgkmcnt(0)
	v_pk_add_f32 v[136:137], v[136:137], v[184:185]
	v_pk_add_f32 v[186:187], v[190:191], v[198:199]
	ds_bpermute_b32 v199, v218, v139
	ds_bpermute_b32 v198, v218, v138
	v_pk_add_f32 v[184:185], v[178:179], v[200:201]
	ds_bpermute_b32 v179, v165, v137
	ds_bpermute_b32 v178, v165, v136
	ds_bpermute_b32 v209, v218, v187
	ds_bpermute_b32 v208, v218, v186
	s_waitcnt lgkmcnt(4)
	v_pk_add_f32 v[198:199], v[138:139], v[198:199]
	s_ashr_i32 s14, s51, 11
	s_waitcnt lgkmcnt(2)
	v_pk_add_f32 v[136:137], v[136:137], v[178:179]
	s_and_b32 s14, s14, -2
	s_waitcnt lgkmcnt(0)
	v_pk_add_f32 v[138:139], v[186:187], v[208:209]
	v_pk_fma_f32 v[208:209], v[136:137], s[36:37], v[170:171] op_sel_hi:[1,0,0]
	ds_bpermute_b32 v201, v165, v199
	v_mul_f32_e32 v136, 0x4b800000, v209
	v_cmp_gt_f32_e32 vcc, s71, v209
	ds_bpermute_b32 v200, v165, v198
	ds_bpermute_b32 v187, v165, v185
	v_cndmask_b32_e32 v136, v209, v136, vcc
	v_rsq_f32_e32 v136, v136
	ds_bpermute_b32 v186, v165, v184
	ds_bpermute_b32 v179, v165, v139
	ds_bpermute_b32 v178, v165, v138
	s_or_b32 s14, s14, s63
	s_ashr_i32 s15, s14, 31
	s_and_b64 s[12:13], exec, s[46:47]
	s_lshl_b64 s[14:15], s[14:15], 19
	v_mul_f32_e32 v137, 0x45800000, v136
	v_lshl_add_u64 v[190:191], v[182:183], 0, s[14:15]
	v_cmp_gt_f32_e64 s[14:15], s71, v208
	v_cndmask_b32_e32 v210, v136, v137, vcc
	s_mov_b64 vcc, s[12:13]
	s_cbranch_vccz .LBB0_470
; #define GAS __attribute__((address_space(1)))
; __device__ __forceinline__ u32x4 rope8(const f32x4& a, const f32x4& b, float sc, const float* tab  , int fq) {
;   float v[8], p[8], o[8];
; #pragma unroll
;   for (int j = 0; j < 4; ++j) { v[j] = a[j] * sc; v[4 + j] = b[j] * sc; }
; #pragma unroll
;   for (int j = 0; j < 8; ++j) p[j] = __shfl_xor(v[j], 32);
;   const f32x4 c0 = *(GAS const f32x4*)(tab + 8 * (fq & 1)), c1 = *(GAS const f32x4*)(tab + 8 * (fq & 1) + 4);
;   const f32x4 s0 = *(GAS const f32x4*)(tab + 16 + 8 * (fq & 1)), s1 = *(GAS const f32x4*)(tab + 16 + 8 * (fq & 1) + 4);
; #pragma unroll
;   for (int j = 0; j < 8; ++j) {
;     const float cc = j < 4 ? c0[j & 3] : c1[j & 3], sn = j < 4 ? s0[j & 3] : s1[j & 3];
;     o[j] = (fq < 2) ? (v[j] * cc - p[j] * sn) : (p[j] * sn + v[j] * cc);
;   }
;   u32x4 w; w.x = pk_bf16(o[0], o[1]); w.y = pk_bf16(o[2], o[3]); w.z = pk_bf16(o[4], o[5]); w.w = pk_bf16(o[6], o[7]); return w;
; }
;   __device__ __forceinline__ void operator()(ACC_T, const Unit& u, int wr, int wc, int fr, int fq) const {
;     ...
;           *(GAS u32x4*)(Kr + (size_t)row * 32 + 8 * fq) = rope8(acc[ai][0][m][0], acc[ai][0][m][1], r, rope + (size_t)s * 32, fq);
	v_and_b32_e32 v136, 0xfcf, v202
	s_cmp_lt_i32 s75, 3
	s_mov_b64 s[12:13], -1
	s_cbranch_scc1 .LBB0_467
	s_cmp_gt_i32 s75, 4
	s_cbranch_scc0 .LBB0_462
	v_lshlrev_b32_e32 v214, 7, v136
	v_mov_b32_e32 v215, v153
	v_lshl_add_u64 v[214:215], v[176:177], 0, v[214:215]
	v_lshlrev_b32_e32 v220, 2, v154
	v_mov_b32_e32 v221, v153
	v_lshl_add_u64 v[214:215], v[214:215], 0, v[220:221]
	global_load_dwordx4 v[220:223], v[214:215], off offset:64
	global_load_dwordx4 v[224:227], v[214:215], off offset:80
	global_load_dwordx4 v[228:231], v[214:215], off
	global_load_dwordx4 v[232:235], v[214:215], off offset:16
	v_pk_mul_f32 v[214:215], v[124:125], v[210:211] op_sel_hi:[1,0]
	v_pk_mul_f32 v[236:237], v[126:127], v[210:211] op_sel_hi:[1,0]
	v_pk_mul_f32 v[238:239], v[120:121], v[210:211] op_sel_hi:[1,0]
	v_pk_mul_f32 v[240:241], v[122:123], v[210:211] op_sel_hi:[1,0]
	ds_bpermute_b32 v242, v165, v214
	ds_bpermute_b32 v243, v165, v215
	ds_bpermute_b32 v244, v165, v236
	ds_bpermute_b32 v245, v165, v237
	ds_bpermute_b32 v246, v165, v238
	ds_bpermute_b32 v247, v165, v239
	ds_bpermute_b32 v248, v165, v240
	ds_bpermute_b32 v249, v165, v241
	v_lshl_add_u64 v[212:213], v[134:135], 0, v[212:213]
	s_mov_b64 s[12:13], 0
	s_waitcnt vmcnt(3) lgkmcnt(6)
	v_pk_mul_f32 v[220:221], v[220:221], v[242:243]
	s_waitcnt lgkmcnt(4)
	v_pk_mul_f32 v[222:223], v[222:223], v[244:245]
	s_waitcnt vmcnt(2) lgkmcnt(2)
	v_pk_mul_f32 v[224:225], v[224:225], v[246:247]
	s_waitcnt lgkmcnt(0)
	v_pk_mul_f32 v[226:227], v[226:227], v[248:249]
	v_cndmask_b32_e64 v221, v221, -v221, s[8:9]
	v_cndmask_b32_e64 v220, v220, -v220, s[8:9]
	v_cndmask_b32_e64 v223, v223, -v223, s[8:9]
	v_cndmask_b32_e64 v222, v222, -v222, s[8:9]
	v_cndmask_b32_e64 v225, v225, -v225, s[8:9]
	v_cndmask_b32_e64 v224, v224, -v224, s[8:9]
	v_cndmask_b32_e64 v227, v227, -v227, s[8:9]
	v_cndmask_b32_e64 v226, v226, -v226, s[8:9]
	s_waitcnt vmcnt(1)
	v_pk_fma_f32 v[214:215], v[214:215], v[228:229], v[220:221]
	v_pk_fma_f32 v[222:223], v[236:237], v[230:231], v[222:223]
	s_waitcnt vmcnt(0)
	v_pk_fma_f32 v[224:225], v[238:239], v[232:233], v[224:225]
	v_pk_fma_f32 v[226:227], v[240:241], v[234:235], v[226:227]
	v_cvt_pk_bf16_f32 v220, v214, v215
	v_cvt_pk_bf16_f32 v221, v222, v223
	v_cvt_pk_bf16_f32 v222, v224, v225
	v_cvt_pk_bf16_f32 v223, v226, v227
	global_store_dwordx4 v[212:213], v[220:223], off

; #define LAS __attribute__((address_space(3)))
;     __host__ __device__ bool next(int i, Unit& u) const {
;         const long L = (long)i * G + c; if (L >= nwg) return false;
;         int wgid = (int)L; { const int q = nwg / NXCD, r = nwg % NXCD, xcd = wgid % NXCD, off = wgid / NXCD; wgid = (xcd < r ? xcd * (q + 1) : r * (q + 1) + (xcd - r) * q) + off; }
;         const int nig = WGM * nN, gid = wgid / nig, fm = gid * WGM, gsz = (nM - fm) < WGM ? (nM - fm) : WGM;
;         u.pm = fm + ((wgid % nig) % gsz); u.pn = (wgid % nig) / gsz; return true;
; template <bool ALIGN = true, class Epi>
; __device__ __forceinline__ void run_gemm(LAS unsigned char* lds, const bf16_t* A, const bf16_t* Bt, int N, int K, const Epi& E) {
;   asm volatile("" : "+s"(N), "+s"(K));
;   pg8::Gemm g{A, Bt, NTOK, N, K};
;   pg8::StaticOrder S; S.init(NTOK, N, (int)gridDim.x, (int)blockIdx.x);
.LBB0_1407:
	s_or_b64 exec, exec, s[46:47]
	s_mov_b64 s[6:7], s[0:1]
	s_load_dwordx2 s[98:99], s[0:1], 0xe8
	s_waitcnt lgkmcnt(0)
	s_barrier
	v_mov_b32_e32 v12, v254
	s_waitcnt vmcnt(0)
	v_mov_b64_e32 v[0:1], s[6:7]
	flat_load_dwordx2 v[140:141], v[0:1] offset:192
	flat_load_dwordx2 v[142:143], v[0:1] offset:424
	s_movk_i32 s7, 0xd00
	s_movk_i32 s6, 0x400
	s_ashr_i32 s8, s7, 31
	s_lshr_b32 s8, s8, 24
	s_add_i32 s7, s7, s8
	s_ashr_i32 s13, s7, 8
	s_lshl_b32 s8, s13, 7
	s_cmp_lt_i32 s2, s8
	s_cselect_b64 s[10:11], -1, 0
	s_cmp_ge_i32 s2, s8
	v_readfirstlane_b32 s9, v12
	s_cbranch_scc1 .LBB0_1409
	s_lshl_b32 s15, s13, 3
	s_abs_i32 s16, s15
	v_cvt_f32_u32_e32 v0, s16
	s_lshr_b32 s12, s3, 29
	s_add_i32 s12, s2, s12
	s_ashr_i32 s14, s12, 3
	v_rcp_iflag_f32_e32 v0, v0
	s_and_b32 s12, s12, -8
	s_sub_i32 s12, s2, s12
	s_lshl_b32 s7, s13, 4
	v_mul_f32_e32 v0, 0x4f7ffffe, v0
	v_cvt_u32_f32_e32 v0, v0
	s_lshr_b32 s17, s12, 31
	s_or_b32 s7, s7, s17
	s_sub_i32 s17, 0, s16
	v_readfirstlane_b32 s18, v0
	s_mul_i32 s7, s7, s12
	s_mul_i32 s17, s17, s18
	s_add_i32 s7, s7, s14
	s_mul_hi_u32 s17, s18, s17
	s_abs_i32 s14, s7
	s_add_i32 s18, s18, s17
	s_mul_hi_u32 s17, s14, s18
	s_mul_i32 s18, s17, s16
	s_xor_b32 s12, s7, s15
	s_sub_i32 s14, s14, s18
	s_ashr_i32 s12, s12, 31
	s_add_i32 s18, s17, 1
	s_sub_i32 s19, s14, s16
	s_cmp_ge_u32 s14, s16
	s_cselect_b32 s17, s18, s17
	s_cselect_b32 s14, s19, s14
	s_add_i32 s18, s17, 1
	s_cmp_ge_u32 s14, s16
	s_cselect_b32 s14, s18, s17
	s_xor_b32 s14, s14, s12
	s_sub_i32 s12, s14, s12
	s_lshl_b32 s14, s12, 3
	s_sub_i32 s16, 0x80, s14
	s_min_i32 s16, s16, 8
	s_abs_i32 s17, s16
	v_cvt_f32_u32_e32 v0, s17
	s_sub_i32 s18, 0, s17
	s_mul_i32 s12, s12, s15
	s_sub_i32 s7, s7, s12
	v_rcp_iflag_f32_e32 v0, v0
	s_abs_i32 s15, s7
	s_xor_b32 s12, s7, s16
	s_ashr_i32 s12, s12, 31
	v_mul_f32_e32 v0, 0x4f7ffffe, v0
	v_cvt_u32_f32_e32 v0, v0
	s_nop 0
	v_readfirstlane_b32 s19, v0
	s_mul_i32 s18, s18, s19
	s_mul_hi_u32 s18, s19, s18
	s_add_i32 s19, s19, s18
	s_mul_hi_u32 s18, s15, s19
	s_mul_i32 s19, s18, s17
	s_sub_i32 s15, s15, s19
	s_add_i32 s19, s18, 1
	s_sub_i32 s20, s15, s17
	s_cmp_ge_u32 s15, s17
	s_cselect_b32 s18, s19, s18
	s_cselect_b32 s15, s20, s15
	s_add_i32 s19, s18, 1
	s_cmp_ge_u32 s15, s17
	s_cselect_b32 s15, s19, s18
	s_xor_b32 s15, s15, s12
	s_sub_i32 s22, s15, s12
	s_mul_i32 s12, s22, s16
	s_sub_i32 s7, s7, s12
	s_add_i32 s12, s7, s14

; #define GAS __attribute__((address_space(1)))
; template <int NP>
; __device__ __forceinline__ void rows_rstd(const float* ssq, float invn, const Unit& u, int wr, int fr, int fq, float (&rs)[2][4]) {
; #pragma unroll
;   for (int ai = 0; ai < 2; ++ai)
; #pragma unroll
;     for (int m = 0; m < 4; ++m) {
;       const int row = erow(u, ai, wr, m, fr);
;       float s;
;       if (NP == 16) {
;         const f32x4 v = *(GAS const f32x4*)(ssq + (size_t)row * 16 + 4 * fq);
;         s = (v[0] + v[1]) + (v[2] + v[3]);
;         s += __shfl_xor(s, 16); s += __shfl_xor(s, 32);
;       } else {
;         const f32x4 v = *(GAS const f32x4*)(ssq + (size_t)row * 4);
;         s = (v[0] + v[1]) + (v[2] + v[3]);
;       }
;       rs[ai][m] = rsqrtf(s * invn + RMS_EPS);
;     }
;   __device__ __forceinline__ void operator()(ACC_T, const Unit& u, int wr, int wc, int fr, int fq) const {
;     if (u.pn == 12 && wc != 0) return;
;     const Params& P = kparams();
;     const float *ssq = P.ssqA, *bfp = P.od_bf; bf16_t *Qc = P.Qc, *Kc = P.Kc, *Vtc = P.Vtc; float* logf = P.logf;
;     float rs[2][4]; rows_rstd<16>(ssq, 1.0f / DM, u, wr, fr, fq, rs);
; #pragma unroll
;     for (int ai = 0; ai < 2; ++ai)
; #pragma unroll
;       for (int m = 0; m < 4; ++m) {
;         const int row = erow(u, ai, wr, m, fr), b = row >> 12, s = row & (SEQ - 1); const float r = rs[ai][m];
.LBB0_1426:
	s_cmp_eq_u32 s22, 12
	s_cselect_b64 s[10:11], -1, 0
	s_and_b64 s[10:11], s[34:35], s[10:11]
	s_and_b64 vcc, exec, s[10:11]
	s_cbranch_vccnz .LBB0_1508
	s_mov_b64 s[10:11], s[0:1]
	s_lshl_b32 s80, s12, 8
	v_mov_b64_e32 v[174:175], s[10:11]
	v_mov_b64_e32 v[128:129], s[98:99]
	s_add_i32 s80, s80, s68
	v_or_b32_e32 v204, s80, v155
	v_or_b32_e32 v196, 16, v204
	v_add_u32_e32 v130, 0x80, v204
	v_mov_b32_e32 v165, v153
	v_ashrrev_i32_e32 v197, 31, v196
	v_ashrrev_i32_e32 v131, 31, v130
	v_or_b32_e32 v192, 32, v204
	v_add_u32_e32 v176, 0x90, v204
	v_lshlrev_b64 v[202:203], 6, v[196:197]
	v_lshlrev_b64 v[130:131], 6, v[130:131]
	v_ashrrev_i32_e32 v193, 31, v192
	v_ashrrev_i32_e32 v177, 31, v176
	flat_load_dwordx2 v[132:133], v[174:175] offset:264
	flat_load_dwordx2 v[134:135], v[174:175] offset:160
	v_or_b32_e32 v184, 48, v204
	v_add_u32_e32 v178, 0xa0, v204
	v_lshlrev_b64 v[194:195], 6, v[192:193]
	v_ashrrev_i32_e32 v205, 31, v204
	v_ashrrev_i32_e32 v185, 31, v184
	v_ashrrev_i32_e32 v179, 31, v178
	v_add_u32_e32 v206, 0xb0, v204
	v_lshlrev_b64 v[208:209], 6, v[204:205]
	v_lshlrev_b64 v[190:191], 6, v[184:185]
	v_ashrrev_i32_e32 v207, 31, v206
	v_lshlrev_b32_e32 v152, 2, v154
	s_cmp_gt_i32 s22, 7
	s_cselect_b64 s[16:17], -1, 0
	s_cmp_gt_u32 s22, 11
	s_cselect_b64 s[60:61], -1, 0
	s_lshl_b32 s97, s22, 8
	s_add_i32 s97, s97, s73
	s_cmp_lt_i32 s22, 4
	v_mov_b32_e32 v167, v153
	s_cselect_b64 s[10:11], -1, 0
	s_ashr_i32 s12, s80, 8
	s_mov_b64 s[62:63], -1
	s_and_b32 s51, s12, -16
	v_lshl_add_u64 v[128:129], v[128:129], 0, v[164:165]
	v_lshl_add_u64 v[180:181], v[128:129], 0, v[202:203]
	v_lshl_add_u64 v[130:131], v[128:129], 0, v[130:131]
	global_load_dwordx4 v[180:183], v[180:181], off
	v_lshl_add_u64 v[186:187], v[128:129], 0, v[194:195]
	global_load_dwordx4 v[220:223], v[130:131], off
	v_lshlrev_b64 v[130:131], 6, v[176:177]
	v_lshl_add_u64 v[130:131], v[128:129], 0, v[130:131]
	global_load_dwordx4 v[186:189], v[186:187], off
	v_lshl_add_u64 v[136:137], v[128:129], 0, v[208:209]
	global_load_dwordx4 v[224:227], v[130:131], off
	v_lshlrev_b64 v[130:131], 6, v[178:179]
	v_lshl_add_u64 v[198:199], v[128:129], 0, v[190:191]
	v_lshl_add_u64 v[130:131], v[128:129], 0, v[130:131]
	global_load_dwordx4 v[136:139], v[136:137], off
	v_and_b32_e32 v178, 64, v216
	global_load_dwordx4 v[198:201], v[198:199], off
	v_xor_b32_e32 v165, 16, v216
	global_load_dwordx4 v[228:231], v[130:131], off
	v_lshlrev_b64 v[130:131], 6, v[206:207]
	v_lshl_add_u64 v[128:129], v[128:129], 0, v[130:131]
	global_load_dwordx4 v[232:235], v[128:129], off
	s_nop 0
	flat_load_dwordx4 v[128:131], v[174:175] offset:520
	flat_load_dwordx2 v[176:177], v[174:175] offset:536
	v_add_u32_e32 v174, 64, v178
	v_xor_b32_e32 v179, 32, v216
	v_cmp_lt_i32_e32 vcc, v165, v174
	s_waitcnt vmcnt(0)
	v_mov_b32_e32 v206, v229
	v_cndmask_b32_e32 v165, v216, v165, vcc
	v_cmp_lt_i32_e32 vcc, v179, v174
	v_mov_b32_e32 v207, v230
	v_mov_b32_e32 v229, v231
	v_cndmask_b32_e32 v174, v216, v179, vcc
	v_lshlrev_b32_e32 v214, 2, v174
	v_lshl_add_u64 v[178:179], v[134:135], 0, v[152:153]
	v_lshl_add_u64 v[174:175], v[132:133], 0, v[152:153]
	v_mov_b32_e32 v132, v137
	v_mov_b32_e32 v133, v138
	v_mov_b32_e32 v137, v139
	v_mov_b32_e32 v134, v181
	v_mov_b32_e32 v135, v182
	v_mov_b32_e32 v181, v183
	v_mov_b32_e32 v138, v187
	v_mov_b32_e32 v139, v188
	v_mov_b32_e32 v187, v189
	v_mov_b32_e32 v182, v199
	v_mov_b32_e32 v183, v200
	v_mov_b32_e32 v199, v201
	v_mov_b32_e32 v188, v221
	v_mov_b32_e32 v189, v222
	v_mov_b32_e32 v221, v223
	v_mov_b32_e32 v200, v225
	v_mov_b32_e32 v201, v226
	v_mov_b32_e32 v225, v227
	v_pk_add_f32 v[132:133], v[132:133], v[136:137]
	v_pk_add_f32 v[134:135], v[134:135], v[180:181]
	v_mov_b32_e32 v210, v233
	v_mov_b32_e32 v211, v234
	v_mov_b32_e32 v233, v235
	v_pk_add_f32 v[136:137], v[138:139], v[186:187]
	v_pk_add_f32 v[138:139], v[182:183], v[198:199]
	v_pk_add_f32 v[180:181], v[188:189], v[220:221]
	v_pk_add_f32 v[182:183], v[200:201], v[224:225]
	v_mov_b32_e32 v198, v134
	v_mov_b32_e32 v199, v132
	v_mov_b32_e32 v132, v135
	v_lshlrev_b32_e32 v165, 2, v165
	v_pk_add_f32 v[186:187], v[206:207], v[228:229]
	v_pk_add_f32 v[188:189], v[210:211], v[232:233]
	v_mov_b32_e32 v134, v138
	v_mov_b32_e32 v135, v136
	v_mov_b32_e32 v136, v139
	v_mov_b32_e32 v138, v182
	v_mov_b32_e32 v139, v180
	v_mov_b32_e32 v180, v183
	v_pk_add_f32 v[132:133], v[198:199], v[132:133]
	v_mov_b32_e32 v182, v188
	v_mov_b32_e32 v183, v186
	v_mov_b32_e32 v186, v189
	v_pk_add_f32 v[134:135], v[134:135], v[136:137]
	v_pk_add_f32 v[136:137], v[138:139], v[180:181]
	ds_bpermute_b32 v181, v165, v133
	ds_bpermute_b32 v180, v165, v132
	v_pk_add_f32 v[138:139], v[182:183], v[186:187]
	ds_bpermute_b32 v183, v165, v135
	ds_bpermute_b32 v182, v165, v134
	ds_bpermute_b32 v187, v165, v137
	s_waitcnt lgkmcnt(0)
	v_pk_add_f32 v[132:133], v[132:133], v[180:181]
	ds_bpermute_b32 v186, v165, v136
	ds_bpermute_b32 v189, v165, v139
	v_pk_add_f32 v[198:199], v[134:135], v[182:183]
	ds_bpermute_b32 v135, v214, v133
	ds_bpermute_b32 v134, v214, v132
	ds_bpermute_b32 v188, v165, v138
	s_waitcnt lgkmcnt(4)
	v_pk_add_f32 v[186:187], v[136:137], v[186:187]
	ds_bpermute_b32 v201, v214, v199
	ds_bpermute_b32 v200, v214, v198
	s_waitcnt lgkmcnt(3)
	v_pk_add_f32 v[132:133], v[132:133], v[134:135]
	s_waitcnt lgkmcnt(2)
	v_pk_add_f32 v[180:181], v[138:139], v[188:189]
	v_pk_fma_f32 v[206:207], v[132:133], s[46:47], v[168:169] op_sel_hi:[1,0,0]
	ds_bpermute_b32 v189, v214, v187
	v_mul_f32_e32 v132, 0x4b800000, v207
	v_cmp_gt_f32_e64 s[14:15], s85, v207
	ds_bpermute_b32 v188, v214, v186
	ds_bpermute_b32 v183, v214, v181
	v_cndmask_b32_e64 v132, v207, v132, s[14:15]
	v_rsq_f32_e32 v132, v132
	ds_bpermute_b32 v182, v214, v180
	s_and_b64 vcc, exec, s[16:17]
	v_lshl_add_u64 v[176:177], v[176:177], 0, v[166:167]
	v_mul_f32_e32 v133, 0x45800000, v132
	v_cmp_gt_f32_e64 s[12:13], s85, v206
	v_cndmask_b32_e64 v165, v132, v133, s[14:15]
	s_cbranch_vccz .LBB0_1435
; #define GAS __attribute__((address_space(1)))
;   __device__ __forceinline__ void operator()(ACC_T, const Unit& u, int wr, int wc, int fr, int fq) const {
;     ...
;         } else if (fq < 2) {
;           f32x4 o0, o1;
;           const f32x4 b0 = *(GAS const f32x4*)(bfp + 8 * fq), b1 = *(GAS const f32x4*)(bfp + 8 * fq + 4);
; #pragma unroll
;           for (int j = 0; j < 4; ++j) {
;             const float x0 = acc[ai][0][m][0][j] * r + b0[j], x1 = acc[ai][0][m][1][j] * r + b1[j];
;             o0[j] = fminf(x0, 0.f) - log1pf(__expf(-fabsf(x0)));
;             o1[j] = fminf(x1, 0.f) - log1pf(__expf(-fabsf(x1)));
;           }
;           *(GAS f32x4*)(logf + (size_t)row * 16 + 8 * fq) = o0; *(GAS f32x4*)(logf + (size_t)row * 16 + 8 * fq + 4) = o1;
	s_mov_b64 s[14:15], -1
	s_and_b64 vcc, exec, s[60:61]
	s_cbranch_vccz .LBB0_1432
	s_and_saveexec_b64 s[14:15], s[6:7]
	s_cbranch_execz .LBB0_1431
	global_load_dwordx4 v[136:139], v[178:179], off
	global_load_dwordx4 v[132:135], v[178:179], off offset:16
	s_waitcnt vmcnt(0)
	v_fma_f32 v152, v124, v165, v136
	v_fma_f32 v167, v125, v165, v137
	v_fma_f32 v207, v126, v165, v138
	v_fma_f32 v210, v127, v165, v139
	v_mul_f32_e64 v211, |v152|, s86
	v_mul_f32_e64 v214, |v167|, s86
	v_mul_f32_e64 v215, |v207|, s86
	v_mul_f32_e64 v220, |v210|, s86
	v_exp_f32_e32 v211, v211
	v_exp_f32_e32 v214, v214
	v_exp_f32_e32 v215, v215
	v_exp_f32_e32 v220, v220
	v_min_f32_e32 v136, 0, v152
	v_min_f32_e32 v137, 0, v167
	v_min_f32_e32 v138, 0, v207
	v_min_f32_e32 v139, 0, v210
	v_add_f32_e32 v221, 1.0, v211
	v_add_f32_e32 v222, 1.0, v214
	v_add_f32_e32 v223, 1.0, v215
	v_add_f32_e32 v224, 1.0, v220
	v_log_f32_e32 v225, v221
	v_log_f32_e32 v226, v222
	v_log_f32_e32 v227, v223
	v_log_f32_e32 v228, v224
	v_add_f32_e32 v229, -1.0, v221
	v_add_f32_e32 v230, -1.0, v222
	v_add_f32_e32 v231, -1.0, v223
	v_add_f32_e32 v232, -1.0, v224
	v_rcp_f32_e32 v233, v229
	v_rcp_f32_e32 v234, v230
	v_rcp_f32_e32 v235, v231
	v_rcp_f32_e32 v236, v232
	v_sub_f32_e32 v152, v136, v211
	v_sub_f32_e32 v167, v137, v214
	v_sub_f32_e32 v207, v138, v215
	v_sub_f32_e32 v210, v139, v220
	v_mul_f32_e32 v233, v211, v233
	v_mul_f32_e32 v234, v214, v234
	v_mul_f32_e32 v235, v215, v235
	v_mul_f32_e32 v236, v220, v236
	v_mul_f32_e32 v225, v225, v233
	v_mul_f32_e32 v226, v226, v234
	v_mul_f32_e32 v227, v227, v235
	v_mul_f32_e32 v228, v228, v236
	v_fmamk_f32 v225, v225, 0xbf317218, v136
	v_fmamk_f32 v226, v226, 0xbf317218, v137
	v_fmamk_f32 v227, v227, 0xbf317218, v138
	v_fmamk_f32 v228, v228, 0xbf317218, v139
	v_cmp_eq_f32_e32 vcc, 0, v229
	s_nop 1
	v_cndmask_b32_e32 v136, v225, v152, vcc
	v_cmp_eq_f32_e32 vcc, 0, v230
	s_nop 1
	v_cndmask_b32_e32 v137, v226, v167, vcc
	v_cmp_eq_f32_e32 vcc, 0, v231
	s_nop 1
	v_cndmask_b32_e32 v138, v227, v207, vcc
	v_cmp_eq_f32_e32 vcc, 0, v232
	s_nop 1
	v_cndmask_b32_e32 v139, v228, v210, vcc
	v_fma_f32 v152, v120, v165, v132
	v_fma_f32 v167, v121, v165, v133
	v_fma_f32 v207, v122, v165, v134
	v_fma_f32 v210, v123, v165, v135
	v_mul_f32_e64 v211, |v152|, s86
	v_mul_f32_e64 v214, |v167|, s86
	v_mul_f32_e64 v215, |v207|, s86
	v_mul_f32_e64 v220, |v210|, s86
	v_exp_f32_e32 v211, v211
	v_exp_f32_e32 v214, v214
	v_exp_f32_e32 v215, v215
	v_exp_f32_e32 v220, v220
	v_min_f32_e32 v132, 0, v152
	v_min_f32_e32 v133, 0, v167
	v_min_f32_e32 v134, 0, v207
	v_min_f32_e32 v135, 0, v210
	v_add_f32_e32 v221, 1.0, v211
	v_add_f32_e32 v222, 1.0, v214
	v_add_f32_e32 v223, 1.0, v215
	v_add_f32_e32 v224, 1.0, v220
	v_log_f32_e32 v225, v221
	v_log_f32_e32 v226, v222
	v_log_f32_e32 v227, v223
	v_log_f32_e32 v228, v224
	v_add_f32_e32 v229, -1.0, v221
	v_add_f32_e32 v230, -1.0, v222
	v_add_f32_e32 v231, -1.0, v223
	v_add_f32_e32 v232, -1.0, v224
	v_rcp_f32_e32 v233, v229
	v_rcp_f32_e32 v234, v230
	v_rcp_f32_e32 v235, v231
	v_rcp_f32_e32 v236, v232
	v_sub_f32_e32 v152, v132, v211
	v_sub_f32_e32 v167, v133, v214
	v_sub_f32_e32 v207, v134, v215
	v_sub_f32_e32 v210, v135, v220
	v_mul_f32_e32 v233, v211, v233
	v_mul_f32_e32 v234, v214, v234
	v_mul_f32_e32 v235, v215, v235
	v_mul_f32_e32 v236, v220, v236
	v_mul_f32_e32 v225, v225, v233
	v_mul_f32_e32 v226, v226, v234
	v_mul_f32_e32 v227, v227, v235
	v_mul_f32_e32 v228, v228, v236
	v_fmamk_f32 v225, v225, 0xbf317218, v132
	v_fmamk_f32 v226, v226, 0xbf317218, v133
	v_fmamk_f32 v227, v227, 0xbf317218, v134
	v_fmamk_f32 v228, v228, 0xbf317218, v135
	v_cmp_eq_f32_e32 vcc, 0, v229
	s_nop 1
	v_cndmask_b32_e32 v132, v225, v152, vcc
	v_cmp_eq_f32_e32 vcc, 0, v230
	s_nop 1
	v_cndmask_b32_e32 v133, v226, v167, vcc
	v_cmp_eq_f32_e32 vcc, 0, v231
	s_nop 1
	v_cndmask_b32_e32 v134, v227, v207, vcc
	v_cmp_eq_f32_e32 vcc, 0, v232
	s_nop 1
	v_cndmask_b32_e32 v135, v228, v210, vcc
	v_lshl_add_u64 v[208:209], v[174:175], 0, v[208:209]
	global_store_dwordx4 v[208:209], v[136:139], off
	global_store_dwordx4 v[208:209], v[132:135], off offset:16

; __global__ void __launch_bounds__(NTHREADS, 2) k_mega(Params Pdummy) {
	.amdhsa_kernel _Z6k_mega6Params
		.amdhsa_group_segment_fixed_size 0
		.amdhsa_private_segment_fixed_size 0
		.amdhsa_kernarg_size 800
		.amdhsa_user_sgpr_count 2
		.amdhsa_user_sgpr_dispatch_ptr 0
		.amdhsa_user_sgpr_queue_ptr 0
		.amdhsa_user_sgpr_kernarg_segment_ptr 1
		.amdhsa_user_sgpr_dispatch_id 0
		.amdhsa_user_sgpr_kernarg_preload_length 0
		.amdhsa_user_sgpr_kernarg_preload_offset 0
		.amdhsa_user_sgpr_private_segment_size 0
		.amdhsa_uses_dynamic_stack 0
		.amdhsa_enable_private_segment 0
		.amdhsa_system_sgpr_workgroup_id_x 1
		.amdhsa_system_sgpr_workgroup_id_y 0
		.amdhsa_system_sgpr_workgroup_id_z 0
		.amdhsa_system_sgpr_workgroup_info 0
		.amdhsa_system_vgpr_workitem_id 2
		.amdhsa_next_free_vgpr 256
		.amdhsa_next_free_sgpr 102
		.amdhsa_accum_offset 256
		.amdhsa_reserve_vcc 1
		.amdhsa_float_round_mode_32 0
		.amdhsa_float_round_mode_16_64 0
		.amdhsa_float_denorm_mode_32 3
		.amdhsa_float_denorm_mode_16_64 3
		.amdhsa_dx10_clamp 1
		.amdhsa_ieee_mode 1
		.amdhsa_fp16_overflow 0
		.amdhsa_tg_split 0
		.amdhsa_exception_fp_ieee_invalid_op 0
		.amdhsa_exception_fp_denorm_src 0
		.amdhsa_exception_fp_ieee_div_zero 0
		.amdhsa_exception_fp_ieee_overflow 0
		.amdhsa_exception_fp_ieee_underflow 0
		.amdhsa_exception_fp_ieee_inexact 0
		.amdhsa_exception_int_div_zero 0
	.end_amdhsa_kernel

; __global__ void __launch_bounds__(NTHREADS, 2) k_mega(Params Pdummy) {
amdhsa.kernels:
  - .agpr_count:     0
    .args:
      - .offset:         0
        .size:           544
        .value_kind:     by_value
      - .offset:         544
        .size:           4
        .value_kind:     hidden_block_count_x
      - .offset:         548
        .size:           4
        .value_kind:     hidden_block_count_y
      - .offset:         552
        .size:           4
        .value_kind:     hidden_block_count_z
      - .offset:         556
        .size:           2
        .value_kind:     hidden_group_size_x
      - .offset:         558
        .size:           2
        .value_kind:     hidden_group_size_y
      - .offset:         560
        .size:           2
        .value_kind:     hidden_group_size_z
      - .offset:         562
        .size:           2
        .value_kind:     hidden_remainder_x
      - .offset:         564
        .size:           2
        .value_kind:     hidden_remainder_y
      - .offset:         566
        .size:           2
        .value_kind:     hidden_remainder_z
      - .offset:         584
        .size:           8
        .value_kind:     hidden_global_offset_x
      - .offset:         592
        .size:           8
        .value_kind:     hidden_global_offset_y
      - .offset:         600
        .size:           8
        .value_kind:     hidden_global_offset_z
      - .offset:         608
        .size:           2
        .value_kind:     hidden_grid_dims
      - .offset:         632
        .size:           8
        .value_kind:     hidden_multigrid_sync_arg
      - .offset:         664
        .size:           4
        .value_kind:     hidden_dynamic_lds_size
    .group_segment_fixed_size: 0
    .kernarg_segment_align: 8
    .kernarg_segment_size: 800
    .language:       OpenCL C
    .language_version:
      - 2
      - 0
    .max_flat_workgroup_size: 512
    .name:           _Z6k_mega6Params
    .private_segment_fixed_size: 0
    .sgpr_count:     108
    .sgpr_spill_count: 2
    .symbol:         _Z6k_mega6Params.kd
    .uniform_work_group_size: 1
    .uses_dynamic_stack: false
    .vgpr_count:     256
    .vgpr_spill_count: 0
    .wavefront_size: 64
